# scan stage 2: per-element uniform-branch ladders replaced by batched fast paths (GLA and SSD); attention bucket lookups branch-free
# speedup vs baseline: 1.0070x; 1.0035x over previous
.LBB0_604:
.LBB0_605:
	v_mul_lo_u32 v20, v132, s54
	v_add3_u32 v20, 0, v20, v133
	s_barrier
	ds_read_b128 v[60:63], v20 offset:61440
	ds_read_b128 v[56:59], v20 offset:61504
	v_add_u32_e32 v20, s79, v130
	v_add_u32_e32 v111, s66, v20
	v_add_u32_e32 v20, s67, v20
	ds_read_b64_tr_b16 v[132:133], v111 offset:0
	ds_read_b64_tr_b16 v[134:135], v111 offset:576
	ds_read_b64_tr_b16 v[100:101], v111 offset:4608
	ds_read_b64_tr_b16 v[102:103], v111 offset:5184
	ds_read_b64_tr_b16 v[76:77], v20 offset:0
	ds_read_b64_tr_b16 v[78:79], v20 offset:576
	ds_read_b64_tr_b16 v[72:73], v20 offset:4608
	ds_read_b64_tr_b16 v[74:75], v20 offset:5184
	ds_read_b64_tr_b16 v[68:69], v20 offset:9216
	ds_read_b64_tr_b16 v[70:71], v20 offset:9792
	ds_read_b64_tr_b16 v[64:65], v20 offset:13824
	ds_read_b64_tr_b16 v[66:67], v20 offset:14400
	s_waitcnt lgkmcnt(0)
	s_and_b64 vcc, exec, s[10:11]
	v_mfma_f32_16x16x32_bf16 v[76:79], v[16:19], v[76:79], 0
	v_mfma_f32_16x16x32_bf16 v[72:75], v[80:83], v[72:75], v[76:79]
	v_mfma_f32_16x16x32_bf16 v[68:71], v[84:87], v[68:71], v[72:75]
	v_mfma_f32_16x16x32_bf16 v[64:67], v[96:99], v[64:67], v[68:71]
	s_waitcnt lgkmcnt(1)
	v_mfma_f32_16x16x32_bf16 v[68:71], v[60:63], v[132:135], 0
	s_waitcnt lgkmcnt(0)
	v_mfma_f32_16x16x32_bf16 v[68:71], v[56:59], v[100:103], v[68:71]
	s_and_b64 vcc, exec, s[24:25]
	s_cbranch_vccz .Lscan_eA_orig
	s_and_b64 vcc, exec, s[10:11]
	s_cbranch_vccnz .Lscan_eA_ssd
	s_lshl_b64 s[12:13], s[30:31], 1
	s_add_u32 s12, s28, s12
	s_addc_u32 s13, s29, s13
	v_mov_b32_e32 v198, v112
	v_mov_b32_e32 v199, 0
	v_lshl_add_u64 v[198:199], s[12:13], 0, v[198:199]
	v_add_u32_e32 v150, s84, v127
	v_add_u32_e32 v151, s84, v131
	v_add_u32_e32 v152, s84, v129
	v_add_u32_e32 v153, s84, v23
	v_add_f32_e32 v196, v64, v68
	v_mad_i64_i32 v[194:195], s[92:93], v150, s3, v[198:199]
	v_cvt_pk_bf16_f32 v196, v196, s0
	global_store_short v[194:195], v196, off
	v_add_f32_e32 v196, v65, v69
	v_mad_i64_i32 v[194:195], s[92:93], v151, s3, v[198:199]
	v_cvt_pk_bf16_f32 v196, v196, s0
	global_store_short v[194:195], v196, off
	v_add_f32_e32 v196, v66, v70
	v_mad_i64_i32 v[194:195], s[92:93], v152, s3, v[198:199]
	v_cvt_pk_bf16_f32 v196, v196, s0
	global_store_short v[194:195], v196, off
	v_add_f32_e32 v196, v67, v71
	v_mad_i64_i32 v[194:195], s[92:93], v153, s3, v[198:199]
	v_cvt_pk_bf16_f32 v196, v196, s0
	global_store_short v[194:195], v196, off
	s_branch .LBB0_647
.Lscan_eA_ssd:
	v_add_u32_e32 v154, s59, v112
	v_add_u32_e32 v155, s64, v112
	v_add_u32_e32 v154, v154, v128
	v_add_u32_e32 v155, v155, v128
	v_lshl_add_u32 v156, v127, 2, s71
	ds_read_u16 v160, v154
	ds_read_u16 v161, v154 offset:144
	ds_read_u16 v162, v154 offset:288
	ds_read_u16 v163, v154 offset:432
	ds_read_u16 v164, v155
	ds_read_u16 v165, v155 offset:144
	ds_read_u16 v166, v155 offset:288
	ds_read_u16 v167, v155 offset:432
	ds_read_b32 v168, v156 offset:256
	ds_read_b32 v169, v156 offset:260
	ds_read_b32 v170, v156 offset:264
	ds_read_b32 v171, v156 offset:268
	s_lshl_b64 s[12:13], s[34:35], 1
	s_add_u32 s12, s28, s12
	s_addc_u32 s13, s29, s13
	v_mov_b32_e32 v198, v112
	v_mov_b32_e32 v199, 0
	v_lshl_add_u64 v[198:199], s[12:13], 0, v[198:199]
	v_add_u32_e32 v150, s84, v127
	v_add_u32_e32 v151, s84, v131
	v_add_u32_e32 v152, s84, v129
	v_add_u32_e32 v153, s84, v23
	v_mov_b32_e32 v184, v110
	v_mov_b32_e32 v186, v110
	v_mov_b32_e32 v188, v110
	v_mov_b32_e32 v190, v110
	s_waitcnt lgkmcnt(0)
	v_mul_f32_e32 v168, 0x3fb8aa3b, v168
	v_mul_f32_e32 v169, 0x3fb8aa3b, v169
	v_mul_f32_e32 v170, 0x3fb8aa3b, v170
	v_mul_f32_e32 v171, 0x3fb8aa3b, v171
	v_exp_f32_e32 v172, v168
	v_exp_f32_e32 v173, v169
	v_exp_f32_e32 v174, v170
	v_exp_f32_e32 v175, v171
	v_lshlrev_b32_e32 v177, 16, v160
	v_lshlrev_b32_e32 v179, 16, v161
	v_lshlrev_b32_e32 v181, 16, v162
	v_lshlrev_b32_e32 v183, 16, v163
	v_mul_f32_e32 v160, 0xbfb8aa3b, v177
	v_mul_f32_e32 v161, 0xbfb8aa3b, v179
	v_mul_f32_e32 v162, 0xbfb8aa3b, v181
	v_mul_f32_e32 v163, 0xbfb8aa3b, v183
	v_exp_f32_e32 v160, v160
	v_exp_f32_e32 v161, v161
	v_exp_f32_e32 v162, v162
	v_exp_f32_e32 v163, v163
	v_lshlrev_b32_e32 v176, 16, v164
	v_lshlrev_b32_e32 v178, 16, v165
	v_lshlrev_b32_e32 v180, 16, v166
	v_lshlrev_b32_e32 v182, 16, v167
	v_add_f32_e32 v160, 1.0, v160
	v_add_f32_e32 v161, 1.0, v161
	v_add_f32_e32 v162, 1.0, v162
	v_add_f32_e32 v163, 1.0, v163
	v_rcp_f32_e32 v185, v160
	v_rcp_f32_e32 v187, v161
	v_rcp_f32_e32 v189, v162
	v_rcp_f32_e32 v191, v163
	v_fma_f32 v164, v64, v172, v68
	v_fma_f32 v165, v65, v173, v69
	v_fma_f32 v166, v66, v174, v70
	v_fma_f32 v167, v67, v175, v71
	v_pk_mul_f32 v[176:177], v[184:185], v[176:177]
	v_pk_mul_f32 v[178:179], v[186:187], v[178:179]
	v_pk_mul_f32 v[180:181], v[188:189], v[180:181]
	v_pk_mul_f32 v[182:183], v[190:191], v[182:183]
	v_add_f32_e32 v164, v176, v164
	v_add_f32_e32 v165, v178, v165
	v_add_f32_e32 v166, v180, v166
	v_add_f32_e32 v167, v182, v167
	v_mul_f32_e32 v164, v164, v177
	v_mul_f32_e32 v165, v165, v179
	v_mul_f32_e32 v166, v166, v181
	v_mul_f32_e32 v167, v167, v183
	v_mad_i64_i32 v[194:195], s[92:93], v150, s3, v[198:199]
	v_cvt_pk_bf16_f32 v196, v164, s0
	global_store_short v[194:195], v196, off
	v_mad_i64_i32 v[194:195], s[92:93], v151, s3, v[198:199]
	v_cvt_pk_bf16_f32 v196, v165, s0
	global_store_short v[194:195], v196, off
	v_mad_i64_i32 v[194:195], s[92:93], v152, s3, v[198:199]
	v_cvt_pk_bf16_f32 v196, v166, s0
	global_store_short v[194:195], v196, off
	v_mad_i64_i32 v[194:195], s[92:93], v153, s3, v[198:199]
	v_cvt_pk_bf16_f32 v196, v167, s0
	global_store_short v[194:195], v196, off
	s_branch .LBB0_647
.Lscan_eA_orig:
	s_and_b64 vcc, exec, s[10:11]
	s_cbranch_vccnz .LBB0_614
	s_mov_b64 s[50:51], 0
	s_and_b64 vcc, exec, s[24:25]
	s_mov_b64 s[12:13], 0
	s_cbranch_vccz .LBB0_608
	s_nop 2
	v_add_f32_e32 v74, v64, v68
	s_mov_b64 s[12:13], -1

.LBB0_647:
	v_add_u32_e32 v23, s80, v130
	v_add_u32_e32 v67, s66, v23
	v_add_u32_e32 v23, s67, v23
	ds_read_b64_tr_b16 v[130:131], v67 offset:0
	ds_read_b64_tr_b16 v[132:133], v67 offset:576
	ds_read_b64_tr_b16 v[112:113], v67 offset:4608
	ds_read_b64_tr_b16 v[114:115], v67 offset:5184
	ds_read_b64_tr_b16 v[100:101], v23 offset:0
	ds_read_b64_tr_b16 v[102:103], v23 offset:576
	ds_read_b64_tr_b16 v[76:77], v23 offset:4608
	ds_read_b64_tr_b16 v[78:79], v23 offset:5184
	ds_read_b64_tr_b16 v[72:73], v23 offset:9216
	ds_read_b64_tr_b16 v[74:75], v23 offset:9792
	ds_read_b64_tr_b16 v[68:69], v23 offset:13824
	ds_read_b64_tr_b16 v[70:71], v23 offset:14400
	s_waitcnt lgkmcnt(0)
	s_and_b64 vcc, exec, s[10:11]
	v_mfma_f32_16x16x32_bf16 v[16:19], v[16:19], v[100:103], 0
	v_mfma_f32_16x16x32_bf16 v[16:19], v[80:83], v[76:79], v[16:19]
	v_mfma_f32_16x16x32_bf16 v[16:19], v[84:87], v[72:75], v[16:19]
	v_mfma_f32_16x16x32_bf16 v[60:63], v[60:63], v[130:133], 0
	v_mfma_f32_16x16x32_bf16 v[16:19], v[96:99], v[68:71], v[16:19]
	v_mfma_f32_16x16x32_bf16 v[56:59], v[56:59], v[112:115], v[60:63]
	s_and_b64 vcc, exec, s[24:25]
	s_cbranch_vccz .Lscan_eB_orig
	s_and_b64 vcc, exec, s[10:11]
	s_cbranch_vccnz .Lscan_eB_ssd
	s_lshl_b64 s[12:13], s[30:31], 1
	s_add_u32 s12, s28, s12
	s_addc_u32 s13, s29, s13
	v_mov_b32_e32 v198, v22
	v_mov_b32_e32 v199, 0
	v_lshl_add_u64 v[198:199], s[12:13], 0, v[198:199]
	s_nop 3
	v_add_f32_e32 v196, v16, v56
	v_mad_i64_i32 v[194:195], s[92:93], v150, s3, v[198:199]
	v_cvt_pk_bf16_f32 v196, v196, s0
	global_store_short v[194:195], v196, off
	v_add_f32_e32 v196, v17, v57
	v_mad_i64_i32 v[194:195], s[92:93], v151, s3, v[198:199]
	v_cvt_pk_bf16_f32 v196, v196, s0
	global_store_short v[194:195], v196, off
	v_add_f32_e32 v196, v18, v58
	v_mad_i64_i32 v[194:195], s[92:93], v152, s3, v[198:199]
	v_cvt_pk_bf16_f32 v196, v196, s0
	global_store_short v[194:195], v196, off
	v_add_f32_e32 v196, v19, v59
	v_mad_i64_i32 v[194:195], s[92:93], v153, s3, v[198:199]
	v_cvt_pk_bf16_f32 v196, v196, s0
	global_store_short v[194:195], v196, off
	s_branch .LBB0_687
.Lscan_eB_ssd:
	v_add_u32_e32 v154, s59, v22
	v_add_u32_e32 v155, s64, v22
	v_add_u32_e32 v154, v154, v128
	v_add_u32_e32 v155, v155, v128
	ds_read_u16 v160, v154
	ds_read_u16 v161, v154 offset:144
	ds_read_u16 v162, v154 offset:288
	ds_read_u16 v163, v154 offset:432
	ds_read_u16 v164, v155
	ds_read_u16 v165, v155 offset:144
	ds_read_u16 v166, v155 offset:288
	ds_read_u16 v167, v155 offset:432
	s_lshl_b64 s[12:13], s[34:35], 1
	s_add_u32 s12, s28, s12
	s_addc_u32 s13, s29, s13
	v_mov_b32_e32 v198, v22
	v_mov_b32_e32 v199, 0
	v_lshl_add_u64 v[198:199], s[12:13], 0, v[198:199]
	v_mov_b32_e32 v184, v110
	v_mov_b32_e32 v186, v110
	v_mov_b32_e32 v188, v110
	v_mov_b32_e32 v190, v110
	s_waitcnt lgkmcnt(0)
	v_lshlrev_b32_e32 v177, 16, v160
	v_lshlrev_b32_e32 v179, 16, v161
	v_lshlrev_b32_e32 v181, 16, v162
	v_lshlrev_b32_e32 v183, 16, v163
	v_mul_f32_e32 v160, 0xbfb8aa3b, v177
	v_mul_f32_e32 v161, 0xbfb8aa3b, v179
	v_mul_f32_e32 v162, 0xbfb8aa3b, v181
	v_mul_f32_e32 v163, 0xbfb8aa3b, v183
	v_exp_f32_e32 v160, v160
	v_exp_f32_e32 v161, v161
	v_exp_f32_e32 v162, v162
	v_exp_f32_e32 v163, v163
	v_lshlrev_b32_e32 v176, 16, v164
	v_lshlrev_b32_e32 v178, 16, v165
	v_lshlrev_b32_e32 v180, 16, v166
	v_lshlrev_b32_e32 v182, 16, v167
	v_add_f32_e32 v160, 1.0, v160
	v_add_f32_e32 v161, 1.0, v161
	v_add_f32_e32 v162, 1.0, v162
	v_add_f32_e32 v163, 1.0, v163
	v_rcp_f32_e32 v185, v160
	v_rcp_f32_e32 v187, v161
	v_rcp_f32_e32 v189, v162
	v_rcp_f32_e32 v191, v163
	v_fma_f32 v164, v16, v172, v56
	v_fma_f32 v165, v17, v173, v57
	v_fma_f32 v166, v18, v174, v58
	v_fma_f32 v167, v19, v175, v59
	v_pk_mul_f32 v[176:177], v[184:185], v[176:177]
	v_pk_mul_f32 v[178:179], v[186:187], v[178:179]
	v_pk_mul_f32 v[180:181], v[188:189], v[180:181]
	v_pk_mul_f32 v[182:183], v[190:191], v[182:183]
	v_add_f32_e32 v164, v176, v164
	v_add_f32_e32 v165, v178, v165
	v_add_f32_e32 v166, v180, v166
	v_add_f32_e32 v167, v182, v167
	v_mul_f32_e32 v164, v164, v177
	v_mul_f32_e32 v165, v165, v179
	v_mul_f32_e32 v166, v166, v181
	v_mul_f32_e32 v167, v167, v183
	v_mad_i64_i32 v[194:195], s[92:93], v150, s3, v[198:199]
	v_cvt_pk_bf16_f32 v196, v164, s0
	global_store_short v[194:195], v196, off
	v_mad_i64_i32 v[194:195], s[92:93], v151, s3, v[198:199]
	v_cvt_pk_bf16_f32 v196, v165, s0
	global_store_short v[194:195], v196, off
	v_mad_i64_i32 v[194:195], s[92:93], v152, s3, v[198:199]
	v_cvt_pk_bf16_f32 v196, v166, s0
	global_store_short v[194:195], v196, off
	v_mad_i64_i32 v[194:195], s[92:93], v153, s3, v[198:199]
	v_cvt_pk_bf16_f32 v196, v167, s0
	global_store_short v[194:195], v196, off
	s_branch .LBB0_687
.Lscan_eB_orig:
	s_and_b64 vcc, exec, s[10:11]
	s_cbranch_vccnz .LBB0_654
	s_mov_b64 s[50:51], 0
	s_and_b64 vcc, exec, s[24:25]
	s_mov_b64 s[12:13], 0
	s_cbranch_vccz .LBB0_650
	s_nop 2
	v_add_f32_e32 v62, v16, v56
	s_mov_b64 s[12:13], -1

.LBB0_2544:
	s_waitcnt lgkmcnt(0)
	ds_read_b128 v[116:119], v219
	ds_read_b128 v[120:123], v219 offset:64
	v_add_u32_e32 v229, s41, v187
	v_cmp_gt_i32_e32 vcc, s40, v229
	v_mov_b32_e32 v0, 0
	s_waitcnt lgkmcnt(0)
	v_mfma_f32_16x16x32_bf16 v[116:119], v[4:7], v[116:119], 0
	v_add_u32_e32 v228, s57, v214
	v_mfma_f32_16x16x32_bf16 v[116:119], v[8:11], v[120:123], v[116:119]
	ds_read_b128 v[120:123], v219 offset:128
	ds_read_b128 v[124:127], v219 offset:192
	s_waitcnt lgkmcnt(1)
	v_mfma_f32_16x16x32_bf16 v[116:119], v[12:15], v[120:123], v[116:119]
	s_waitcnt lgkmcnt(0)
	v_mfma_f32_16x16x32_bf16 v[116:119], v[16:19], v[124:127], v[116:119]
	v_add_u32_e32 v0, 0x20000, v228
	ds_read_b32 v0, v0
	s_waitcnt lgkmcnt(0)
	v_cndmask_b32_e32 v0, 0, v0, vcc
	v_sub_u32_e32 v2, s54, v0
	v_max_i32_e32 v0, 0, v2
	v_min_i32_e32 v0, 0x7f, v0
	v_lshl_add_u32 v0, v0, 2, 0
	v_add_u32_e32 v0, 0x22800, v0
	ds_read_b32 v0, v0
	s_waitcnt lgkmcnt(0)
	v_lshlrev_b32_e32 v0, 4, v0
.LBB0_2548:
	ds_read_b128 v[120:123], v219 offset:4352
	ds_read_b128 v[124:127], v219 offset:4416
	v_lshl_add_u32 v0, v0, 2, v191
	s_waitcnt lgkmcnt(1)
	v_mfma_f32_16x16x32_bf16 v[120:123], v[4:7], v[120:123], 0
	s_waitcnt lgkmcnt(0)
	v_mfma_f32_16x16x32_bf16 v[120:123], v[8:11], v[124:127], v[120:123]
	ds_read_b128 v[124:127], v219 offset:4480
	ds_read_b128 v[128:131], v219 offset:4544
	s_waitcnt lgkmcnt(1)
	v_mfma_f32_16x16x32_bf16 v[124:127], v[12:15], v[124:127], v[120:123]
	s_nop 3
	ds_read_b128 v[120:123], v0
	s_waitcnt lgkmcnt(1)
	v_mfma_f32_16x16x32_bf16 v[124:127], v[16:19], v[128:131], v[124:127]
	v_add_u32_e32 v0, 16, v229
	v_cmp_gt_i32_e64 s[6:7], s40, v0
	v_mov_b32_e32 v0, 0
	v_add_u32_e32 v0, 0x20040, v228
	ds_read_b32 v0, v0
	s_waitcnt lgkmcnt(0)
	v_cndmask_b32_e64 v0, 0, v0, s[6:7]
	v_sub_u32_e32 v2, s54, v0
	v_max_i32_e32 v0, 0, v2
	v_min_i32_e32 v0, 0x7f, v0
	v_lshl_add_u32 v0, v0, 2, 0
	v_add_u32_e32 v0, 0x22800, v0
	ds_read_b32 v0, v0
	s_waitcnt lgkmcnt(0)
	v_lshlrev_b32_e32 v0, 4, v0
.LBB0_2552:
	v_lshl_add_u32 v0, v0, 2, v191
	ds_read_b128 v[128:131], v0
	v_add_f32_e32 v0, v118, v122
	v_add_f32_e32 v3, v117, v121
	v_cndmask_b32_e32 v117, v220, v0, vcc
	v_add_f32_e32 v0, v119, v123
	v_cndmask_b32_e32 v118, v220, v0, vcc
	s_waitcnt lgkmcnt(0)
	v_add_f32_e32 v0, v124, v128
	v_cndmask_b32_e64 v119, v220, v0, s[6:7]
	v_add_f32_e32 v0, v125, v129
	v_add_f32_e32 v2, v116, v120
	v_cndmask_b32_e64 v120, v220, v0, s[6:7]
	v_add_f32_e32 v0, v126, v130
	v_cndmask_b32_e32 v2, v220, v2, vcc
	v_cndmask_b32_e64 v121, v220, v0, s[6:7]
	v_add_f32_e32 v0, v127, v131
	v_cndmask_b32_e64 v122, v220, v0, s[6:7]
	v_max_f32_e32 v0, v2, v119
	v_cndmask_b32_e32 v116, v220, v3, vcc
	s_nop 0
	v_max_f32_dpp v0, v0, v0 quad_perm:[1,0,3,2] row_mask:0xf bank_mask:0xf bound_ctrl:1
	s_nop 1
	v_max_f32_dpp v0, v0, v0 quad_perm:[2,3,0,1] row_mask:0xf bank_mask:0xf bound_ctrl:1
	s_nop 1
	v_max_f32_dpp v0, v0, v0 row_half_mirror row_mask:0xf bank_mask:0xf bound_ctrl:1
	s_nop 1
	v_mov_b32_dpp v3, v0 row_mirror row_mask:0xf bank_mask:0xf bound_ctrl:1
	v_max3_f32 v0, v233, v0, v3
	v_sub_f32_e32 v2, v2, v0
	v_sub_f32_e32 v3, v233, v0
	v_mul_f32_e32 v2, 0x3fb8aa3b, v2
	v_mul_f32_e32 v123, 0x3fb8aa3b, v3
	v_exp_f32_e32 v3, v2
	v_sub_f32_e32 v2, v119, v0
	v_mul_f32_e32 v2, 0x3fb8aa3b, v2
	v_exp_f32_e32 v159, v2
	v_cvt_pk_bf16_f32 v2, v3, s0
	ds_write_b16 v221, v2 offset:8704
	v_exp_f32_e32 v161, v123
	v_cvt_pk_bf16_f32 v2, v159, s0
	ds_write_b16 v221, v2 offset:8736
	v_max_f32_e32 v2, v116, v120
	v_cmp_neq_f32_e32 vcc, 1.0, v161
	s_nop 0
	v_max_f32_dpp v2, v2, v2 quad_perm:[1,0,3,2] row_mask:0xf bank_mask:0xf bound_ctrl:1
	s_nop 1
	v_max_f32_dpp v2, v2, v2 quad_perm:[2,3,0,1] row_mask:0xf bank_mask:0xf bound_ctrl:1
	s_nop 1
	v_max_f32_dpp v2, v2, v2 row_half_mirror row_mask:0xf bank_mask:0xf bound_ctrl:1
	s_nop 1
	v_mov_b32_dpp v119, v2 row_mirror row_mask:0xf bank_mask:0xf bound_ctrl:1
	v_max3_f32 v226, v232, v2, v119
	v_sub_f32_e32 v2, v232, v226
	v_mul_f32_e32 v119, 0x3fb8aa3b, v2
	v_sub_f32_e32 v2, v116, v226
	v_mul_f32_e32 v2, 0x3fb8aa3b, v2
	v_sub_f32_e32 v116, v120, v226
	v_exp_f32_e32 v2, v2
	v_mul_f32_e32 v116, 0x3fb8aa3b, v116
	v_exp_f32_e32 v158, v116
	v_exp_f32_e32 v160, v119
	v_cvt_pk_bf16_f32 v116, v2, s0
	ds_write_b16 v221, v116 offset:8784
	v_cvt_pk_bf16_f32 v116, v158, s0
	ds_write_b16 v221, v116 offset:8816
	v_max_f32_e32 v116, v117, v121
	v_cmp_neq_f32_e64 s[6:7], 1.0, v160
	s_or_b64 s[6:7], vcc, s[6:7]
	v_max_f32_dpp v116, v116, v116 quad_perm:[1,0,3,2] row_mask:0xf bank_mask:0xf bound_ctrl:1
	s_nop 1
	v_max_f32_dpp v116, v116, v116 quad_perm:[2,3,0,1] row_mask:0xf bank_mask:0xf bound_ctrl:1
	s_nop 1
	v_max_f32_dpp v116, v116, v116 row_half_mirror row_mask:0xf bank_mask:0xf bound_ctrl:1
	s_nop 1
	v_mov_b32_dpp v119, v116 row_mirror row_mask:0xf bank_mask:0xf bound_ctrl:1
	v_max3_f32 v227, v231, v116, v119
	v_sub_f32_e32 v117, v117, v227
	v_mul_f32_e32 v117, 0x3fb8aa3b, v117
	v_exp_f32_e32 v181, v117
	v_sub_f32_e32 v117, v121, v227
	v_mul_f32_e32 v117, 0x3fb8aa3b, v117
	v_exp_f32_e32 v183, v117
	v_sub_f32_e32 v116, v231, v227
	v_mul_f32_e32 v116, 0x3fb8aa3b, v116
	v_exp_f32_e32 v185, v116
	v_cvt_pk_bf16_f32 v116, v181, s0
	ds_write_b16 v221, v116 offset:8864
	v_cvt_pk_bf16_f32 v116, v183, s0
	ds_write_b16 v221, v116 offset:8896
	v_max_f32_e32 v116, v118, v122
	v_cmp_neq_f32_e32 vcc, 1.0, v185
	s_or_b64 s[6:7], s[6:7], vcc
	v_max_f32_dpp v116, v116, v116 quad_perm:[1,0,3,2] row_mask:0xf bank_mask:0xf bound_ctrl:1
	s_nop 1
	v_max_f32_dpp v116, v116, v116 quad_perm:[2,3,0,1] row_mask:0xf bank_mask:0xf bound_ctrl:1
	s_nop 1
	v_max_f32_dpp v116, v116, v116 row_half_mirror row_mask:0xf bank_mask:0xf bound_ctrl:1
	s_nop 1
	v_mov_b32_dpp v117, v116 row_mirror row_mask:0xf bank_mask:0xf bound_ctrl:1
	v_max3_f32 v224, v230, v116, v117
	v_sub_f32_e32 v117, v118, v224
	v_mul_f32_e32 v117, 0x3fb8aa3b, v117
	v_exp_f32_e32 v180, v117
	v_sub_f32_e32 v117, v122, v224
	v_mul_f32_e32 v117, 0x3fb8aa3b, v117
	v_exp_f32_e32 v182, v117
	v_sub_f32_e32 v116, v230, v224
	v_mul_f32_e32 v116, 0x3fb8aa3b, v116
	v_exp_f32_e32 v184, v116
	v_cvt_pk_bf16_f32 v116, v180, s0
	ds_write_b16 v221, v116 offset:8944
	v_cvt_pk_bf16_f32 v116, v182, s0
	ds_write_b16 v221, v116 offset:8976
	s_waitcnt lgkmcnt(0)
	ds_read_b128 v[116:119], v222 offset:8704
	ds_read_b64_tr_b16 v[148:149], v193 offset:0
	ds_read_b64_tr_b16 v[150:151], v193 offset:1088
	ds_read_b64_tr_b16 v[144:145], v193 offset:32
	ds_read_b64_tr_b16 v[146:147], v193 offset:1120
	ds_read_b64_tr_b16 v[140:141], v193 offset:64
	ds_read_b64_tr_b16 v[142:143], v193 offset:1152
	ds_read_b64_tr_b16 v[136:137], v193 offset:96
	ds_read_b64_tr_b16 v[138:139], v193 offset:1184
	ds_read_b64_tr_b16 v[132:133], v193 offset:128
	ds_read_b64_tr_b16 v[134:135], v193 offset:1216
	ds_read_b64_tr_b16 v[128:129], v193 offset:160
	ds_read_b64_tr_b16 v[130:131], v193 offset:1248
	ds_read_b64_tr_b16 v[124:125], v193 offset:192
	ds_read_b64_tr_b16 v[126:127], v193 offset:1280
	ds_read_b64_tr_b16 v[120:121], v193 offset:224
	ds_read_b64_tr_b16 v[122:123], v193 offset:1312
	s_waitcnt lgkmcnt(0)
	v_cmp_neq_f32_e32 vcc, 1.0, v184
	s_or_b64 vcc, s[6:7], vcc
	s_cbranch_vccz .LBB0_2554
	v_mov_b32_e32 v230, v185
	v_mov_b32_e32 v231, v184
	v_mov_b32_e32 v232, v161
	v_mov_b32_e32 v233, v160
	v_pk_mul_f32 v[62:63], v[62:63], v[230:231]
	v_pk_mul_f32 v[60:61], v[60:61], v[232:233]
	v_pk_mul_f32 v[58:59], v[58:59], v[230:231]
	v_pk_mul_f32 v[56:57], v[56:57], v[232:233]
	v_pk_mul_f32 v[54:55], v[54:55], v[230:231]
	v_pk_mul_f32 v[52:53], v[52:53], v[232:233]
	v_pk_mul_f32 v[50:51], v[50:51], v[230:231]
	v_pk_mul_f32 v[48:49], v[48:49], v[232:233]
	v_pk_mul_f32 v[46:47], v[46:47], v[230:231]
	v_pk_mul_f32 v[44:45], v[44:45], v[232:233]
	v_pk_mul_f32 v[42:43], v[42:43], v[230:231]
	v_pk_mul_f32 v[40:41], v[40:41], v[232:233]
	v_pk_mul_f32 v[38:39], v[38:39], v[230:231]
	v_pk_mul_f32 v[36:37], v[36:37], v[232:233]
	v_pk_mul_f32 v[34:35], v[34:35], v[230:231]
	v_pk_mul_f32 v[32:33], v[32:33], v[232:233]

.LBB0_2573:
	s_waitcnt lgkmcnt(0)
	ds_read_b128 v[116:119], v219
	ds_read_b128 v[120:123], v219 offset:64
	v_add_u32_e32 v2, 32, v229
	v_cmp_gt_i32_e32 vcc, s40, v2
	v_mov_b32_e32 v2, 0
	s_waitcnt lgkmcnt(1)
	v_mfma_f32_16x16x32_bf16 v[116:119], v[4:7], v[116:119], 0
	s_waitcnt lgkmcnt(0)
	v_mfma_f32_16x16x32_bf16 v[116:119], v[8:11], v[120:123], v[116:119]
	ds_read_b128 v[120:123], v219 offset:128
	ds_read_b128 v[124:127], v219 offset:192
	s_waitcnt lgkmcnt(1)
	v_mfma_f32_16x16x32_bf16 v[116:119], v[12:15], v[120:123], v[116:119]
	s_waitcnt lgkmcnt(0)
	v_mfma_f32_16x16x32_bf16 v[116:119], v[16:19], v[124:127], v[116:119]
	v_add_u32_e32 v2, 0x20080, v228
	ds_read_b32 v2, v2
	s_waitcnt lgkmcnt(0)
	v_cndmask_b32_e32 v2, 0, v2, vcc
	v_sub_u32_e32 v3, s54, v2
	v_max_i32_e32 v2, 0, v3
	v_min_i32_e32 v2, 0x7f, v2
	v_lshl_add_u32 v2, v2, 2, 0
	v_add_u32_e32 v2, 0x22800, v2
	ds_read_b32 v2, v2
	s_waitcnt lgkmcnt(0)
	v_lshlrev_b32_e32 v2, 4, v2
.LBB0_2577:
	ds_read_b128 v[120:123], v219 offset:4352
	ds_read_b128 v[124:127], v219 offset:4416
	v_lshl_add_u32 v2, v2, 2, v191
	s_waitcnt lgkmcnt(1)
	v_mfma_f32_16x16x32_bf16 v[120:123], v[4:7], v[120:123], 0
	s_waitcnt lgkmcnt(0)
	v_mfma_f32_16x16x32_bf16 v[120:123], v[8:11], v[124:127], v[120:123]
	ds_read_b128 v[124:127], v219 offset:4480
	ds_read_b128 v[128:131], v219 offset:4544
	s_waitcnt lgkmcnt(1)
	v_mfma_f32_16x16x32_bf16 v[124:127], v[12:15], v[124:127], v[120:123]
	s_nop 3
	ds_read_b128 v[120:123], v2
	s_waitcnt lgkmcnt(1)
	v_mfma_f32_16x16x32_bf16 v[124:127], v[16:19], v[128:131], v[124:127]
	v_add_u32_e32 v2, 48, v229
	v_cmp_gt_i32_e64 s[6:7], s40, v2
	v_mov_b32_e32 v2, 0
	v_add_u32_e32 v2, 0x200c0, v228
	ds_read_b32 v2, v2
	s_waitcnt lgkmcnt(0)
	v_cndmask_b32_e64 v2, 0, v2, s[6:7]
	v_sub_u32_e32 v3, s54, v2
	v_max_i32_e32 v2, 0, v3
	v_min_i32_e32 v2, 0x7f, v2
	v_lshl_add_u32 v2, v2, 2, 0
	v_add_u32_e32 v2, 0x22800, v2
	ds_read_b32 v2, v2
	s_waitcnt lgkmcnt(0)
	v_lshlrev_b32_e32 v2, 4, v2
.LBB0_2581:
	v_lshl_add_u32 v2, v2, 2, v191
	ds_read_b128 v[128:131], v2
	v_add_f32_e32 v2, v118, v122
	v_add_f32_e32 v3, v116, v120
	v_add_f32_e32 v116, v117, v121
	v_cndmask_b32_e32 v117, v220, v2, vcc
	v_add_f32_e32 v2, v119, v123
	v_cndmask_b32_e32 v118, v220, v2, vcc
	s_waitcnt lgkmcnt(0)
	v_add_f32_e32 v2, v124, v128
	v_cndmask_b32_e32 v3, v220, v3, vcc
	v_cndmask_b32_e64 v2, v220, v2, s[6:7]
	v_max_f32_e32 v122, v3, v2
	v_add_f32_e32 v119, v125, v129
	v_cndmask_b32_e32 v116, v220, v116, vcc
	v_max_f32_dpp v122, v122, v122 quad_perm:[1,0,3,2] row_mask:0xf bank_mask:0xf bound_ctrl:1
	v_cndmask_b32_e64 v119, v220, v119, s[6:7]
	v_add_f32_e32 v120, v126, v130
	v_max_f32_dpp v122, v122, v122 quad_perm:[2,3,0,1] row_mask:0xf bank_mask:0xf bound_ctrl:1
	v_cndmask_b32_e64 v120, v220, v120, s[6:7]
	v_add_f32_e32 v121, v127, v131
	v_max_f32_dpp v122, v122, v122 row_half_mirror row_mask:0xf bank_mask:0xf bound_ctrl:1
	v_cndmask_b32_e64 v121, v220, v121, s[6:7]
	s_nop 0
	v_mov_b32_dpp v123, v122 row_mirror row_mask:0xf bank_mask:0xf bound_ctrl:1
	v_max3_f32 v233, v0, v122, v123
	v_sub_f32_e32 v3, v3, v233
	v_mul_f32_e32 v3, 0x3fb8aa3b, v3
	v_sub_f32_e32 v2, v2, v233
	v_exp_f32_e32 v3, v3
	v_mul_f32_e32 v2, 0x3fb8aa3b, v2
	v_exp_f32_e32 v159, v2
	v_sub_f32_e32 v0, v0, v233
	v_mul_f32_e32 v0, 0x3fb8aa3b, v0
	v_exp_f32_e32 v161, v0
	v_cvt_pk_bf16_f32 v0, v3, s0
	ds_write_b16 v221, v0 offset:8704
	v_cvt_pk_bf16_f32 v0, v159, s0
	ds_write_b16 v221, v0 offset:8736
	v_max_f32_e32 v0, v116, v119
	v_cmp_neq_f32_e32 vcc, 1.0, v161
	s_nop 0
	v_max_f32_dpp v0, v0, v0 quad_perm:[1,0,3,2] row_mask:0xf bank_mask:0xf bound_ctrl:1
	s_nop 1
	v_max_f32_dpp v0, v0, v0 quad_perm:[2,3,0,1] row_mask:0xf bank_mask:0xf bound_ctrl:1
	s_nop 1
	v_max_f32_dpp v0, v0, v0 row_half_mirror row_mask:0xf bank_mask:0xf bound_ctrl:1
	s_nop 1
	v_mov_b32_dpp v2, v0 row_mirror row_mask:0xf bank_mask:0xf bound_ctrl:1
	v_max3_f32 v232, v226, v0, v2
	v_sub_f32_e32 v2, v116, v232
	v_mul_f32_e32 v2, 0x3fb8aa3b, v2
	v_sub_f32_e32 v116, v119, v232
	v_exp_f32_e32 v2, v2
	v_mul_f32_e32 v116, 0x3fb8aa3b, v116
	v_exp_f32_e32 v158, v116
	v_sub_f32_e32 v0, v226, v232
	v_mul_f32_e32 v0, 0x3fb8aa3b, v0
	v_exp_f32_e32 v160, v0
	v_cvt_pk_bf16_f32 v0, v2, s0
	ds_write_b16 v221, v0 offset:8784
	v_cvt_pk_bf16_f32 v0, v158, s0
	ds_write_b16 v221, v0 offset:8816
	v_max_f32_e32 v0, v117, v120
	v_cmp_neq_f32_e64 s[6:7], 1.0, v160
	s_or_b64 s[6:7], vcc, s[6:7]
	v_max_f32_dpp v0, v0, v0 quad_perm:[1,0,3,2] row_mask:0xf bank_mask:0xf bound_ctrl:1
	s_nop 1
	v_max_f32_dpp v0, v0, v0 quad_perm:[2,3,0,1] row_mask:0xf bank_mask:0xf bound_ctrl:1
	s_nop 1
	v_max_f32_dpp v0, v0, v0 row_half_mirror row_mask:0xf bank_mask:0xf bound_ctrl:1
	s_nop 1
	v_mov_b32_dpp v116, v0 row_mirror row_mask:0xf bank_mask:0xf bound_ctrl:1
	v_max3_f32 v231, v227, v0, v116
	v_sub_f32_e32 v116, v117, v231
	v_mul_f32_e32 v116, 0x3fb8aa3b, v116
	v_exp_f32_e32 v181, v116
	v_sub_f32_e32 v116, v120, v231
	v_mul_f32_e32 v116, 0x3fb8aa3b, v116
	v_exp_f32_e32 v183, v116
	v_sub_f32_e32 v0, v227, v231
	v_mul_f32_e32 v0, 0x3fb8aa3b, v0
	v_exp_f32_e32 v185, v0
	v_cvt_pk_bf16_f32 v0, v181, s0
	ds_write_b16 v221, v0 offset:8864
	v_cvt_pk_bf16_f32 v0, v183, s0
	ds_write_b16 v221, v0 offset:8896
	v_max_f32_e32 v0, v118, v121
	v_cmp_neq_f32_e32 vcc, 1.0, v185
	s_or_b64 s[6:7], s[6:7], vcc
	v_max_f32_dpp v0, v0, v0 quad_perm:[1,0,3,2] row_mask:0xf bank_mask:0xf bound_ctrl:1
	s_nop 1
	v_max_f32_dpp v0, v0, v0 quad_perm:[2,3,0,1] row_mask:0xf bank_mask:0xf bound_ctrl:1
	s_nop 1
	v_max_f32_dpp v0, v0, v0 row_half_mirror row_mask:0xf bank_mask:0xf bound_ctrl:1
	s_nop 1
	v_mov_b32_dpp v116, v0 row_mirror row_mask:0xf bank_mask:0xf bound_ctrl:1
	v_max3_f32 v230, v224, v0, v116
	v_sub_f32_e32 v116, v118, v230
	v_mul_f32_e32 v116, 0x3fb8aa3b, v116
	v_exp_f32_e32 v180, v116
	v_sub_f32_e32 v116, v121, v230
	v_mul_f32_e32 v116, 0x3fb8aa3b, v116
	v_exp_f32_e32 v182, v116
	v_sub_f32_e32 v0, v224, v230
	v_mul_f32_e32 v0, 0x3fb8aa3b, v0
	v_exp_f32_e32 v184, v0
	v_cvt_pk_bf16_f32 v0, v180, s0
	ds_write_b16 v221, v0 offset:8944
	v_cvt_pk_bf16_f32 v0, v182, s0
	ds_write_b16 v221, v0 offset:8976
	s_waitcnt lgkmcnt(0)
	ds_read_b128 v[116:119], v222 offset:8704
	ds_read_b64_tr_b16 v[148:149], v193 offset:0
	ds_read_b64_tr_b16 v[150:151], v193 offset:1088
	ds_read_b64_tr_b16 v[144:145], v193 offset:32
	ds_read_b64_tr_b16 v[146:147], v193 offset:1120
	ds_read_b64_tr_b16 v[140:141], v193 offset:64
	ds_read_b64_tr_b16 v[142:143], v193 offset:1152
	ds_read_b64_tr_b16 v[136:137], v193 offset:96
	ds_read_b64_tr_b16 v[138:139], v193 offset:1184
	ds_read_b64_tr_b16 v[132:133], v193 offset:128
	ds_read_b64_tr_b16 v[134:135], v193 offset:1216
	ds_read_b64_tr_b16 v[128:129], v193 offset:160
	ds_read_b64_tr_b16 v[130:131], v193 offset:1248
	ds_read_b64_tr_b16 v[124:125], v193 offset:192
	ds_read_b64_tr_b16 v[126:127], v193 offset:1280
	ds_read_b64_tr_b16 v[120:121], v193 offset:224
	ds_read_b64_tr_b16 v[122:123], v193 offset:1312
	s_waitcnt lgkmcnt(0)
	v_cmp_neq_f32_e32 vcc, 1.0, v184
	s_or_b64 vcc, s[6:7], vcc
	s_cbranch_vccz .LBB0_2583
	v_mov_b32_e32 v226, v185
	v_mov_b32_e32 v227, v184
	v_mov_b32_e32 v228, v161
	v_mov_b32_e32 v229, v160
	v_pk_mul_f32 v[62:63], v[62:63], v[226:227]
	v_pk_mul_f32 v[60:61], v[60:61], v[228:229]
	v_pk_mul_f32 v[58:59], v[58:59], v[226:227]
	v_pk_mul_f32 v[56:57], v[56:57], v[228:229]
	v_pk_mul_f32 v[54:55], v[54:55], v[226:227]
	v_pk_mul_f32 v[52:53], v[52:53], v[228:229]
	v_pk_mul_f32 v[50:51], v[50:51], v[226:227]
	v_pk_mul_f32 v[48:49], v[48:49], v[228:229]
	v_pk_mul_f32 v[46:47], v[46:47], v[226:227]
	v_pk_mul_f32 v[44:45], v[44:45], v[228:229]
	v_pk_mul_f32 v[42:43], v[42:43], v[226:227]
	v_pk_mul_f32 v[40:41], v[40:41], v[228:229]
	v_pk_mul_f32 v[38:39], v[38:39], v[226:227]
	v_pk_mul_f32 v[36:37], v[36:37], v[228:229]
	v_pk_mul_f32 v[34:35], v[34:35], v[226:227]
	v_pk_mul_f32 v[32:33], v[32:33], v[228:229]
